# also nt: the gb gate loads of the second P3 GEMM epilogue (read exactly once)
# speedup vs baseline: 1.0130x; 1.0015x over previous
.LBB0_600:
	s_lshl_b32 s3, s3, 8
	v_mov_b32_e32 v112, v205
	v_mov_b32_e32 v113, v202
	s_lshl_b32 s7, s7, 8
	s_add_i32 s3, s3, s86
	s_or_b32 s7, s7, s87
	v_add_u32_e32 v230, s3, v112
	v_lshl_add_u32 v228, v113, 3, s7
	v_ashrrev_i32_e32 v231, 31, v230
	v_ashrrev_i32_e32 v229, 31, v228
	v_lshlrev_b64 v[112:113], 10, v[230:231]
	v_lshl_add_u64 v[112:113], v[112:113], 0, v[228:229]
	v_readlane_b32 s24, v254, 2
	v_lshlrev_b64 v[112:113], 1, v[112:113]
	v_readlane_b32 s25, v254, 3
	v_lshl_add_u64 v[114:115], s[78:79], 0, v[112:113]
	global_load_dwordx4 v[184:187], v[114:115], off
	v_lshl_add_u64 v[112:113], s[24:25], 0, v[112:113]
	global_load_dwordx4 v[188:191], v[112:113], off nt
	global_load_dwordx4 v[172:175], v[114:115], off offset:256
	global_load_dwordx4 v[180:183], v[112:113], off offset:256 nt
	v_add_u32_e32 v236, 16, v230
	v_ashrrev_i32_e32 v237, 31, v236
	v_lshlrev_b64 v[112:113], 10, v[236:237]
	v_lshl_add_u64 v[112:113], v[112:113], 0, v[228:229]
	v_lshlrev_b64 v[112:113], 1, v[112:113]
	v_lshl_add_u64 v[114:115], s[78:79], 0, v[112:113]
	v_lshl_add_u64 v[112:113], s[24:25], 0, v[112:113]
	global_load_dwordx4 v[168:171], v[114:115], off
	global_load_dwordx4 v[176:179], v[112:113], off nt
	global_load_dwordx4 v[156:159], v[114:115], off offset:256
	global_load_dwordx4 v[164:167], v[112:113], off offset:256 nt
	v_lshlrev_b64 v[238:239], 11, v[230:231]
	v_add_u32_e32 v234, 32, v230
	v_ashrrev_i32_e32 v235, 31, v234
	v_lshlrev_b64 v[112:113], 10, v[234:235]
	v_lshl_add_u64 v[112:113], v[112:113], 0, v[228:229]
	v_lshlrev_b64 v[112:113], 1, v[112:113]
	v_add_u32_e32 v232, 48, v230
	v_lshl_add_u64 v[114:115], s[78:79], 0, v[112:113]
	v_lshl_add_u64 v[112:113], s[24:25], 0, v[112:113]
	v_ashrrev_i32_e32 v233, 31, v232
	global_load_dwordx4 v[152:155], v[114:115], off
	global_load_dwordx4 v[160:163], v[112:113], off nt
	global_load_dwordx4 v[136:139], v[114:115], off offset:256
	global_load_dwordx4 v[148:151], v[112:113], off offset:256 nt
	v_lshlrev_b64 v[112:113], 10, v[232:233]
	v_lshl_add_u64 v[112:113], v[112:113], 0, v[228:229]
	v_lshlrev_b64 v[112:113], 1, v[112:113]
	v_lshl_add_u64 v[114:115], s[78:79], 0, v[112:113]
	v_lshl_add_u64 v[120:121], s[24:25], 0, v[112:113]
	global_load_dwordx4 v[128:131], v[114:115], off
	global_load_dwordx4 v[140:143], v[120:121], off nt
	s_nop 0
	global_load_dwordx4 v[112:115], v[114:115], off offset:256
	s_nop 0
	global_load_dwordx4 v[120:123], v[120:121], off offset:256 nt
	s_and_b64 vcc, exec, s[4:5]
	s_waitcnt vmcnt(0)
	v_lshlrev_b32_e32 v200, 16, v189
	v_and_b32_e32 v201, 0xffff0000, v189
	v_lshlrev_b32_e32 v189, 16, v190
	v_mul_f32_e32 v189, 0xbfb8aa3b, v189
	v_exp_f32_e32 v189, v189
	v_and_b32_e32 v198, 0xffff0000, v188
	v_and_b32_e32 v231, 0xffff0000, v190
	v_lshlrev_b32_e32 v192, 16, v188
	v_add_f32_e32 v189, 1.0, v189
	v_rcp_f32_e32 v190, v189
	v_mul_f32_e32 v189, 0xbfb8aa3b, v198
	v_lshlrev_b32_e32 v198, 16, v184
	v_and_b32_e32 v199, 0xffff0000, v184
	v_mul_f32_e32 v184, 0xbfb8aa3b, v231
	v_mul_f32_e32 v188, 0xbfb8aa3b, v192
	v_exp_f32_e32 v184, v184
	v_exp_f32_e32 v188, v188
	v_exp_f32_e32 v189, v189
	v_lshlrev_b32_e32 v240, 16, v191
	v_add_f32_e32 v184, 1.0, v184
	v_and_b32_e32 v241, 0xffff0000, v191
	v_add_f32_e32 v188, 1.0, v188
	v_add_f32_e32 v189, 1.0, v189
	v_rcp_f32_e32 v191, v184
	v_mul_f32_e32 v184, 0xbfb8aa3b, v200
	v_rcp_f32_e32 v188, v188
	v_rcp_f32_e32 v189, v189
	v_exp_f32_e32 v184, v184
	v_pk_fma_f32 v[144:145], v[144:145], v[188:189], v[198:199]
	v_lshlrev_b32_e32 v188, 16, v186
	v_and_b32_e32 v189, 0xffff0000, v186
	v_add_f32_e32 v184, 1.0, v184
	v_pk_fma_f32 v[132:133], v[132:133], v[190:191], v[188:189]
	v_rcp_f32_e32 v188, v184
	v_mul_f32_e32 v184, 0xbfb8aa3b, v240
	v_mul_f32_e32 v186, 0xbfb8aa3b, v201
	v_lshlrev_b32_e32 v190, 16, v185
	v_and_b32_e32 v191, 0xffff0000, v185
	v_mul_f32_e32 v185, 0xbfb8aa3b, v241
	v_exp_f32_e32 v184, v184
	v_exp_f32_e32 v186, v186
	v_exp_f32_e32 v185, v185
	v_cvt_pk_bf16_f32 v144, v144, v145
	v_add_f32_e32 v184, 1.0, v184
	v_add_f32_e32 v186, 1.0, v186
	v_add_f32_e32 v185, 1.0, v185
	v_rcp_f32_e32 v184, v184
	v_rcp_f32_e32 v189, v186
	v_rcp_f32_e32 v185, v185
	v_lshlrev_b32_e32 v186, 16, v187
	v_and_b32_e32 v187, 0xffff0000, v187
	v_pk_fma_f32 v[146:147], v[146:147], v[188:189], v[190:191]
	v_pk_fma_f32 v[134:135], v[134:135], v[184:185], v[186:187]
	v_cvt_pk_bf16_f32 v145, v146, v147
	v_cvt_pk_bf16_f32 v146, v132, v133
	v_cvt_pk_bf16_f32 v147, v134, v135
	v_lshl_add_u64 v[134:135], s[78:79], 0, v[238:239]
	v_lshlrev_b64 v[132:133], 1, v[228:229]
	v_lshl_add_u64 v[134:135], v[134:135], 0, v[132:133]
	global_store_dwordx4 v[134:135], v[144:147], off
	v_lshlrev_b32_e32 v184, 16, v181
	v_and_b32_e32 v185, 0xffff0000, v181
	v_lshlrev_b32_e32 v144, 16, v180
	v_and_b32_e32 v145, 0xffff0000, v180
	v_mul_f32_e32 v144, 0xbfb8aa3b, v144
	v_mul_f32_e32 v145, 0xbfb8aa3b, v145
	v_exp_f32_e32 v144, v144
	v_exp_f32_e32 v145, v145
	v_lshlrev_b32_e32 v146, 16, v182
	v_and_b32_e32 v147, 0xffff0000, v182
	v_add_f32_e32 v144, 1.0, v144
	v_add_f32_e32 v145, 1.0, v145
	v_rcp_f32_e32 v144, v144
	v_rcp_f32_e32 v145, v145
	v_lshlrev_b32_e32 v180, 16, v172
	v_and_b32_e32 v181, 0xffff0000, v172
	v_mul_f32_e32 v146, 0xbfb8aa3b, v146
	v_pk_fma_f32 v[124:125], v[124:125], v[144:145], v[180:181]
	v_mul_f32_e32 v144, 0xbfb8aa3b, v147
	v_exp_f32_e32 v146, v146
	v_exp_f32_e32 v144, v144
	v_lshlrev_b32_e32 v182, 16, v183
	v_and_b32_e32 v145, 0xffff0000, v174
	v_add_f32_e32 v146, 1.0, v146
	v_add_f32_e32 v144, 1.0, v144
	v_rcp_f32_e32 v146, v146
	v_rcp_f32_e32 v147, v144
	v_lshlrev_b32_e32 v144, 16, v174
	v_and_b32_e32 v183, 0xffff0000, v183
	v_lshlrev_b32_e32 v172, 16, v173
	v_pk_fma_f32 v[144:145], v[116:117], v[146:147], v[144:145]
	v_mul_f32_e32 v117, 0xbfb8aa3b, v182
	v_exp_f32_e32 v117, v117
	v_mul_f32_e32 v116, 0xbfb8aa3b, v184
	v_exp_f32_e32 v116, v116
	v_and_b32_e32 v173, 0xffff0000, v173
	v_add_f32_e32 v117, 1.0, v117
	v_rcp_f32_e32 v146, v117
	v_mul_f32_e32 v117, 0xbfb8aa3b, v185
	v_exp_f32_e32 v117, v117
	v_add_f32_e32 v116, 1.0, v116
	v_rcp_f32_e32 v116, v116
	v_add_f32_e32 v117, 1.0, v117
	v_rcp_f32_e32 v117, v117
	s_nop 0
	v_pk_fma_f32 v[126:127], v[126:127], v[116:117], v[172:173]
	v_mul_f32_e32 v116, 0xbfb8aa3b, v183
	v_exp_f32_e32 v116, v116
	v_and_b32_e32 v117, 0xffff0000, v175
	v_add_f32_e32 v116, 1.0, v116
	v_rcp_f32_e32 v147, v116
	v_lshlrev_b32_e32 v116, 16, v175
	v_pk_fma_f32 v[146:147], v[118:119], v[146:147], v[116:117]
	v_cvt_pk_bf16_f32 v116, v124, v125
	v_cvt_pk_bf16_f32 v117, v126, v127
	v_cvt_pk_bf16_f32 v118, v144, v145
	v_cvt_pk_bf16_f32 v119, v146, v147
	global_store_dwordx4 v[134:135], v[116:119], off offset:256
	v_lshlrev_b32_e32 v124, 16, v178
	v_and_b32_e32 v125, 0xffff0000, v178
	v_lshlrev_b32_e32 v118, 16, v176
	v_and_b32_e32 v119, 0xffff0000, v176
	v_mul_f32_e32 v118, 0xbfb8aa3b, v118
	v_mul_f32_e32 v119, 0xbfb8aa3b, v119
	v_exp_f32_e32 v118, v118
	v_exp_f32_e32 v119, v119
	v_lshlrev_b32_e32 v126, 16, v168
	v_and_b32_e32 v127, 0xffff0000, v168
	v_add_f32_e32 v118, 1.0, v118
	v_add_f32_e32 v119, 1.0, v119
	v_rcp_f32_e32 v118, v118
	v_rcp_f32_e32 v119, v119
	v_mul_f32_e32 v124, 0xbfb8aa3b, v124
	v_exp_f32_e32 v124, v124
	v_lshlrev_b32_e32 v144, 16, v179
	v_pk_fma_f32 v[108:109], v[108:109], v[118:119], v[126:127]
	v_mul_f32_e32 v118, 0xbfb8aa3b, v125
	v_exp_f32_e32 v118, v118
	v_add_f32_e32 v124, 1.0, v124
	v_rcp_f32_e32 v124, v124
	v_and_b32_e32 v119, 0xffff0000, v170
	v_add_f32_e32 v118, 1.0, v118
	v_rcp_f32_e32 v125, v118
	v_lshlrev_b32_e32 v118, 16, v170
	v_lshlrev_b32_e32 v134, 16, v177
	v_and_b32_e32 v135, 0xffff0000, v177
	v_pk_fma_f32 v[118:119], v[104:105], v[124:125], v[118:119]
	v_mul_f32_e32 v105, 0xbfb8aa3b, v144
	v_exp_f32_e32 v105, v105
	v_mul_f32_e32 v104, 0xbfb8aa3b, v134
	v_exp_f32_e32 v104, v104
	v_and_b32_e32 v145, 0xffff0000, v179
	v_add_f32_e32 v105, 1.0, v105
	v_rcp_f32_e32 v124, v105
	v_mul_f32_e32 v105, 0xbfb8aa3b, v135
	v_exp_f32_e32 v105, v105
	v_add_f32_e32 v104, 1.0, v104
	v_rcp_f32_e32 v104, v104
	v_lshlrev_b32_e32 v126, 16, v169
	v_add_f32_e32 v105, 1.0, v105
	v_rcp_f32_e32 v105, v105
	v_and_b32_e32 v127, 0xffff0000, v169
	v_lshlrev_b64 v[116:117], 11, v[236:237]
	v_pk_fma_f32 v[110:111], v[110:111], v[104:105], v[126:127]
	v_mul_f32_e32 v104, 0xbfb8aa3b, v145
	v_exp_f32_e32 v104, v104
	v_and_b32_e32 v105, 0xffff0000, v171
	v_add_u32_e32 v126, 0xa0, v230
	v_ashrrev_i32_e32 v127, 31, v126
	v_add_f32_e32 v104, 1.0, v104
	v_rcp_f32_e32 v125, v104
	v_lshlrev_b32_e32 v104, 16, v171
	v_pk_fma_f32 v[124:125], v[106:107], v[124:125], v[104:105]
	v_cvt_pk_bf16_f32 v104, v108, v109
	v_lshl_add_u64 v[108:109], s[78:79], 0, v[116:117]
	v_cvt_pk_bf16_f32 v105, v110, v111
	v_cvt_pk_bf16_f32 v106, v118, v119
	v_cvt_pk_bf16_f32 v107, v124, v125
	v_lshl_add_u64 v[108:109], v[108:109], 0, v[132:133]
	global_store_dwordx4 v[108:109], v[104:107], off
	v_lshlrev_b32_e32 v110, 16, v156
	v_and_b32_e32 v111, 0xffff0000, v156
	v_lshlrev_b32_e32 v104, 16, v164
	v_and_b32_e32 v105, 0xffff0000, v164
	v_mul_f32_e32 v104, 0xbfb8aa3b, v104
	v_mul_f32_e32 v105, 0xbfb8aa3b, v105
	v_exp_f32_e32 v104, v104
	v_exp_f32_e32 v105, v105
	v_lshlrev_b32_e32 v106, 16, v166
	v_and_b32_e32 v107, 0xffff0000, v166
	v_add_f32_e32 v104, 1.0, v104
	v_add_f32_e32 v105, 1.0, v105
	v_rcp_f32_e32 v104, v104
	v_rcp_f32_e32 v105, v105
	v_mul_f32_e32 v106, 0xbfb8aa3b, v106
	v_exp_f32_e32 v106, v106
	v_lshlrev_b32_e32 v118, 16, v167
	v_pk_fma_f32 v[100:101], v[100:101], v[104:105], v[110:111]
	v_mul_f32_e32 v104, 0xbfb8aa3b, v107
	v_exp_f32_e32 v104, v104
	v_add_f32_e32 v106, 1.0, v106
	v_rcp_f32_e32 v106, v106
	v_and_b32_e32 v105, 0xffff0000, v158
	v_add_f32_e32 v104, 1.0, v104
	v_rcp_f32_e32 v107, v104
	v_lshlrev_b32_e32 v104, 16, v158
	v_lshlrev_b32_e32 v116, 16, v165
	v_and_b32_e32 v117, 0xffff0000, v165
	v_pk_fma_f32 v[104:105], v[96:97], v[106:107], v[104:105]
	v_mul_f32_e32 v97, 0xbfb8aa3b, v118
	v_exp_f32_e32 v97, v97
	v_mul_f32_e32 v96, 0xbfb8aa3b, v116
	v_exp_f32_e32 v96, v96
	v_and_b32_e32 v119, 0xffff0000, v167
	v_add_f32_e32 v97, 1.0, v97
	v_rcp_f32_e32 v106, v97
	v_mul_f32_e32 v97, 0xbfb8aa3b, v117
	v_exp_f32_e32 v97, v97
	v_add_f32_e32 v96, 1.0, v96
	v_rcp_f32_e32 v96, v96
	v_lshlrev_b32_e32 v110, 16, v157
	v_add_f32_e32 v97, 1.0, v97
	v_rcp_f32_e32 v97, v97
	v_and_b32_e32 v111, 0xffff0000, v157
	v_add_u32_e32 v124, 0xb0, v230
	v_ashrrev_i32_e32 v125, 31, v124
	v_pk_fma_f32 v[102:103], v[102:103], v[96:97], v[110:111]
	v_mul_f32_e32 v96, 0xbfb8aa3b, v119
	v_exp_f32_e32 v96, v96
	v_and_b32_e32 v97, 0xffff0000, v159
	v_add_f32_e32 v96, 1.0, v96
	v_rcp_f32_e32 v107, v96
	v_lshlrev_b32_e32 v96, 16, v159
	v_pk_fma_f32 v[106:107], v[98:99], v[106:107], v[96:97]
	v_cvt_pk_bf16_f32 v96, v100, v101
	v_cvt_pk_bf16_f32 v97, v102, v103
	v_cvt_pk_bf16_f32 v98, v104, v105
	v_cvt_pk_bf16_f32 v99, v106, v107
	global_store_dwordx4 v[108:109], v[96:99], off offset:256
	v_lshlrev_b32_e32 v100, 16, v162
	v_and_b32_e32 v101, 0xffff0000, v162
	v_lshlrev_b32_e32 v98, 16, v160
	v_and_b32_e32 v99, 0xffff0000, v160
	v_mul_f32_e32 v98, 0xbfb8aa3b, v98
	v_mul_f32_e32 v99, 0xbfb8aa3b, v99
	v_exp_f32_e32 v98, v98
	v_exp_f32_e32 v99, v99
	v_lshlrev_b32_e32 v102, 16, v152
	v_and_b32_e32 v103, 0xffff0000, v152
	v_add_f32_e32 v98, 1.0, v98
	v_add_f32_e32 v99, 1.0, v99
	v_rcp_f32_e32 v98, v98
	v_rcp_f32_e32 v99, v99
	v_mul_f32_e32 v100, 0xbfb8aa3b, v100
	v_exp_f32_e32 v100, v100
	v_lshlrev_b32_e32 v106, 16, v163
	v_pk_fma_f32 v[92:93], v[92:93], v[98:99], v[102:103]
	v_mul_f32_e32 v98, 0xbfb8aa3b, v101
	v_exp_f32_e32 v98, v98
	v_add_f32_e32 v100, 1.0, v100
	v_rcp_f32_e32 v100, v100
	v_and_b32_e32 v99, 0xffff0000, v154
	v_add_f32_e32 v98, 1.0, v98
	v_rcp_f32_e32 v101, v98
	v_lshlrev_b32_e32 v98, 16, v154
	v_lshlrev_b32_e32 v104, 16, v161
	v_and_b32_e32 v105, 0xffff0000, v161
	v_pk_fma_f32 v[98:99], v[88:89], v[100:101], v[98:99]
	v_mul_f32_e32 v89, 0xbfb8aa3b, v106
	v_exp_f32_e32 v89, v89
	v_mul_f32_e32 v88, 0xbfb8aa3b, v104
	v_exp_f32_e32 v88, v88
	v_and_b32_e32 v107, 0xffff0000, v163
	v_add_f32_e32 v89, 1.0, v89
	v_rcp_f32_e32 v100, v89
	v_mul_f32_e32 v89, 0xbfb8aa3b, v105
	v_exp_f32_e32 v89, v89
	v_add_f32_e32 v88, 1.0, v88
	v_rcp_f32_e32 v88, v88
	v_lshlrev_b32_e32 v102, 16, v153
	v_add_f32_e32 v89, 1.0, v89
	v_rcp_f32_e32 v89, v89
	v_and_b32_e32 v103, 0xffff0000, v153
	v_lshlrev_b64 v[96:97], 11, v[234:235]
	v_pk_fma_f32 v[94:95], v[94:95], v[88:89], v[102:103]
	v_mul_f32_e32 v88, 0xbfb8aa3b, v107
	v_exp_f32_e32 v88, v88
	v_and_b32_e32 v89, 0xffff0000, v155
	v_add_f32_e32 v88, 1.0, v88
	v_rcp_f32_e32 v101, v88
	v_lshlrev_b32_e32 v88, 16, v155
	v_pk_fma_f32 v[100:101], v[90:91], v[100:101], v[88:89]
	v_cvt_pk_bf16_f32 v88, v92, v93
	v_lshl_add_u64 v[92:93], s[78:79], 0, v[96:97]
	v_cvt_pk_bf16_f32 v89, v94, v95
	v_cvt_pk_bf16_f32 v90, v98, v99
	v_cvt_pk_bf16_f32 v91, v100, v101
	v_lshl_add_u64 v[92:93], v[92:93], 0, v[132:133]
	global_store_dwordx4 v[92:93], v[88:91], off
	v_lshlrev_b32_e32 v94, 16, v136
	v_and_b32_e32 v95, 0xffff0000, v136
	v_lshlrev_b32_e32 v88, 16, v148
	v_and_b32_e32 v89, 0xffff0000, v148
	v_mul_f32_e32 v88, 0xbfb8aa3b, v88
	v_mul_f32_e32 v89, 0xbfb8aa3b, v89
	v_exp_f32_e32 v88, v88
	v_exp_f32_e32 v89, v89
	v_lshlrev_b32_e32 v90, 16, v150
	v_and_b32_e32 v91, 0xffff0000, v150
	v_add_f32_e32 v88, 1.0, v88
	v_add_f32_e32 v89, 1.0, v89
	v_rcp_f32_e32 v88, v88
	v_rcp_f32_e32 v89, v89
	v_mul_f32_e32 v90, 0xbfb8aa3b, v90
	v_exp_f32_e32 v90, v90
	v_lshlrev_b32_e32 v98, 16, v151
	v_pk_fma_f32 v[84:85], v[84:85], v[88:89], v[94:95]
	v_mul_f32_e32 v88, 0xbfb8aa3b, v91
	v_exp_f32_e32 v88, v88
	v_add_f32_e32 v90, 1.0, v90
	v_rcp_f32_e32 v90, v90
	v_and_b32_e32 v89, 0xffff0000, v138
	v_add_f32_e32 v88, 1.0, v88
	v_rcp_f32_e32 v91, v88
	v_lshlrev_b32_e32 v88, 16, v138
	v_lshlrev_b32_e32 v96, 16, v149
	v_and_b32_e32 v97, 0xffff0000, v149
	v_pk_fma_f32 v[88:89], v[80:81], v[90:91], v[88:89]
	v_mul_f32_e32 v81, 0xbfb8aa3b, v98
	v_exp_f32_e32 v81, v81
	v_mul_f32_e32 v80, 0xbfb8aa3b, v96
	v_exp_f32_e32 v80, v80
	v_and_b32_e32 v99, 0xffff0000, v151
	v_add_f32_e32 v81, 1.0, v81
	v_rcp_f32_e32 v90, v81
	v_mul_f32_e32 v81, 0xbfb8aa3b, v97
	v_exp_f32_e32 v81, v81
	v_add_f32_e32 v80, 1.0, v80
	v_rcp_f32_e32 v80, v80
	v_lshlrev_b32_e32 v94, 16, v137
	v_add_f32_e32 v81, 1.0, v81
	v_rcp_f32_e32 v81, v81
	v_and_b32_e32 v95, 0xffff0000, v137
	v_pk_fma_f32 v[86:87], v[86:87], v[80:81], v[94:95]
	v_mul_f32_e32 v80, 0xbfb8aa3b, v99
	v_exp_f32_e32 v80, v80
	v_and_b32_e32 v81, 0xffff0000, v139
	v_add_f32_e32 v80, 1.0, v80
	v_rcp_f32_e32 v91, v80
	v_lshlrev_b32_e32 v80, 16, v139
	v_pk_fma_f32 v[90:91], v[82:83], v[90:91], v[80:81]
	v_cvt_pk_bf16_f32 v80, v84, v85
	v_cvt_pk_bf16_f32 v81, v86, v87
	v_cvt_pk_bf16_f32 v82, v88, v89
	v_cvt_pk_bf16_f32 v83, v90, v91
	global_store_dwordx4 v[92:93], v[80:83], off offset:256
	v_lshlrev_b32_e32 v84, 16, v142
	v_and_b32_e32 v85, 0xffff0000, v142
	v_lshlrev_b32_e32 v82, 16, v140
	v_and_b32_e32 v83, 0xffff0000, v140
	v_mul_f32_e32 v82, 0xbfb8aa3b, v82
	v_mul_f32_e32 v83, 0xbfb8aa3b, v83
	v_exp_f32_e32 v82, v82
	v_exp_f32_e32 v83, v83
	v_lshlrev_b32_e32 v86, 16, v128
	v_and_b32_e32 v87, 0xffff0000, v128
	v_add_f32_e32 v82, 1.0, v82
	v_add_f32_e32 v83, 1.0, v83
	v_rcp_f32_e32 v82, v82
	v_rcp_f32_e32 v83, v83
	v_mul_f32_e32 v84, 0xbfb8aa3b, v84
	v_exp_f32_e32 v84, v84
	v_lshlrev_b32_e32 v90, 16, v143
	v_pk_fma_f32 v[76:77], v[76:77], v[82:83], v[86:87]
	v_mul_f32_e32 v82, 0xbfb8aa3b, v85
	v_exp_f32_e32 v82, v82
	v_add_f32_e32 v84, 1.0, v84
	v_rcp_f32_e32 v84, v84
	v_and_b32_e32 v83, 0xffff0000, v130
	v_add_f32_e32 v82, 1.0, v82
	v_rcp_f32_e32 v85, v82
	v_lshlrev_b32_e32 v82, 16, v130
	v_lshlrev_b32_e32 v88, 16, v141
	v_and_b32_e32 v89, 0xffff0000, v141
	v_pk_fma_f32 v[82:83], v[72:73], v[84:85], v[82:83]
	v_mul_f32_e32 v73, 0xbfb8aa3b, v90
	v_exp_f32_e32 v73, v73
	v_mul_f32_e32 v72, 0xbfb8aa3b, v88
	v_exp_f32_e32 v72, v72
	v_and_b32_e32 v91, 0xffff0000, v143
	v_add_f32_e32 v73, 1.0, v73
	v_rcp_f32_e32 v84, v73
	v_mul_f32_e32 v73, 0xbfb8aa3b, v89
	v_exp_f32_e32 v73, v73
	v_add_f32_e32 v72, 1.0, v72
	v_rcp_f32_e32 v72, v72
	v_lshlrev_b32_e32 v86, 16, v129
	v_add_f32_e32 v73, 1.0, v73
	v_rcp_f32_e32 v73, v73
	v_and_b32_e32 v87, 0xffff0000, v129
	v_lshlrev_b64 v[80:81], 11, v[232:233]
	v_add_u32_e32 v130, 0x80, v230
	v_pk_fma_f32 v[78:79], v[78:79], v[72:73], v[86:87]
	v_mul_f32_e32 v72, 0xbfb8aa3b, v91
	v_exp_f32_e32 v72, v72
	v_and_b32_e32 v73, 0xffff0000, v131
	v_add_u32_e32 v128, 0x90, v230
	v_ashrrev_i32_e32 v129, 31, v128
	v_add_f32_e32 v72, 1.0, v72
	v_rcp_f32_e32 v85, v72
	v_lshlrev_b32_e32 v72, 16, v131
	v_ashrrev_i32_e32 v131, 31, v130
	v_pk_fma_f32 v[84:85], v[74:75], v[84:85], v[72:73]
	v_cvt_pk_bf16_f32 v72, v76, v77
	v_lshl_add_u64 v[76:77], s[78:79], 0, v[80:81]
	v_cvt_pk_bf16_f32 v73, v78, v79
	v_cvt_pk_bf16_f32 v74, v82, v83
	v_cvt_pk_bf16_f32 v75, v84, v85
	v_lshl_add_u64 v[76:77], v[76:77], 0, v[132:133]
	global_store_dwordx4 v[76:77], v[72:75], off
	v_lshlrev_b32_e32 v78, 16, v112
	v_and_b32_e32 v79, 0xffff0000, v112
	v_lshlrev_b32_e32 v72, 16, v120
	v_and_b32_e32 v73, 0xffff0000, v120
	v_mul_f32_e32 v72, 0xbfb8aa3b, v72
	v_mul_f32_e32 v73, 0xbfb8aa3b, v73
	v_exp_f32_e32 v72, v72
	v_exp_f32_e32 v73, v73
	v_lshlrev_b32_e32 v74, 16, v122
	v_and_b32_e32 v75, 0xffff0000, v122
	v_add_f32_e32 v72, 1.0, v72
	v_add_f32_e32 v73, 1.0, v73
	v_rcp_f32_e32 v72, v72
	v_rcp_f32_e32 v73, v73
	v_mul_f32_e32 v74, 0xbfb8aa3b, v74
	v_exp_f32_e32 v74, v74
	v_lshlrev_b32_e32 v82, 16, v123
	v_pk_fma_f32 v[68:69], v[68:69], v[72:73], v[78:79]
	v_mul_f32_e32 v72, 0xbfb8aa3b, v75
	v_exp_f32_e32 v72, v72
	v_add_f32_e32 v74, 1.0, v74
	v_rcp_f32_e32 v74, v74
	v_and_b32_e32 v73, 0xffff0000, v114
	v_add_f32_e32 v72, 1.0, v72
	v_rcp_f32_e32 v75, v72
	v_lshlrev_b32_e32 v72, 16, v114
	v_lshlrev_b32_e32 v80, 16, v121
	v_and_b32_e32 v81, 0xffff0000, v121
	v_pk_fma_f32 v[72:73], v[64:65], v[74:75], v[72:73]
	v_mul_f32_e32 v65, 0xbfb8aa3b, v82
	v_exp_f32_e32 v65, v65
	v_mul_f32_e32 v64, 0xbfb8aa3b, v80
	v_exp_f32_e32 v64, v64
	v_and_b32_e32 v83, 0xffff0000, v123
	v_add_f32_e32 v65, 1.0, v65
	v_rcp_f32_e32 v74, v65
	v_mul_f32_e32 v65, 0xbfb8aa3b, v81
	v_exp_f32_e32 v65, v65
	v_add_f32_e32 v64, 1.0, v64
	v_rcp_f32_e32 v64, v64
	v_lshlrev_b32_e32 v78, 16, v113
	v_add_f32_e32 v65, 1.0, v65
	v_rcp_f32_e32 v65, v65
	v_and_b32_e32 v79, 0xffff0000, v113
	v_pk_fma_f32 v[70:71], v[70:71], v[64:65], v[78:79]
	v_mul_f32_e32 v64, 0xbfb8aa3b, v83
	v_exp_f32_e32 v64, v64
	v_and_b32_e32 v65, 0xffff0000, v115
	v_add_f32_e32 v64, 1.0, v64
	v_rcp_f32_e32 v75, v64
	v_lshlrev_b32_e32 v64, 16, v115
	v_pk_fma_f32 v[74:75], v[66:67], v[74:75], v[64:65]
	v_cvt_pk_bf16_f32 v64, v68, v69
	v_cvt_pk_bf16_f32 v65, v70, v71
	v_cvt_pk_bf16_f32 v66, v72, v73
	v_cvt_pk_bf16_f32 v67, v74, v75
	global_store_dwordx4 v[76:77], v[64:67], off offset:256
	s_nop 1
	v_lshlrev_b64 v[64:65], 10, v[130:131]
	v_lshl_add_u64 v[64:65], v[64:65], 0, v[228:229]
	v_lshlrev_b64 v[64:65], 1, v[64:65]
	v_lshl_add_u64 v[66:67], s[78:79], 0, v[64:65]
	v_lshl_add_u64 v[64:65], s[24:25], 0, v[64:65]
	global_load_dwordx4 v[120:123], v[66:67], off
	global_load_dwordx4 v[134:137], v[64:65], off nt
	global_load_dwordx4 v[112:115], v[66:67], off offset:256
	global_load_dwordx4 v[116:119], v[64:65], off offset:256 nt
	v_lshlrev_b64 v[64:65], 10, v[128:129]
	v_lshl_add_u64 v[64:65], v[64:65], 0, v[228:229]
	v_lshlrev_b64 v[64:65], 1, v[64:65]
	v_lshl_add_u64 v[66:67], s[78:79], 0, v[64:65]
	v_lshl_add_u64 v[64:65], s[24:25], 0, v[64:65]
	global_load_dwordx4 v[104:107], v[66:67], off
	global_load_dwordx4 v[108:111], v[64:65], off nt
	global_load_dwordx4 v[96:99], v[66:67], off offset:256
	global_load_dwordx4 v[100:103], v[64:65], off offset:256 nt
	v_lshlrev_b64 v[64:65], 10, v[126:127]
	v_lshl_add_u64 v[64:65], v[64:65], 0, v[228:229]
	v_lshlrev_b64 v[64:65], 1, v[64:65]
	v_lshl_add_u64 v[66:67], s[78:79], 0, v[64:65]
	v_lshl_add_u64 v[64:65], s[24:25], 0, v[64:65]
	global_load_dwordx4 v[88:91], v[66:67], off
	global_load_dwordx4 v[92:95], v[64:65], off nt
	global_load_dwordx4 v[80:83], v[66:67], off offset:256
	global_load_dwordx4 v[84:87], v[64:65], off offset:256 nt
	v_lshlrev_b64 v[64:65], 10, v[124:125]
	v_lshl_add_u64 v[64:65], v[64:65], 0, v[228:229]
	v_lshlrev_b64 v[130:131], 11, v[130:131]
	v_lshlrev_b64 v[64:65], 1, v[64:65]
	v_lshl_add_u64 v[66:67], s[78:79], 0, v[64:65]
	v_lshl_add_u64 v[68:69], s[24:25], 0, v[64:65]
	global_load_dwordx4 v[72:75], v[66:67], off
	global_load_dwordx4 v[76:79], v[68:69], off nt
	s_nop 0
	global_load_dwordx4 v[64:67], v[66:67], off offset:256
	s_nop 0
	global_load_dwordx4 v[68:71], v[68:69], off offset:256 nt
	s_mov_b64 s[24:25], -1
	s_waitcnt vmcnt(0)
	v_lshlrev_b32_e32 v140, 16, v135
	v_and_b32_e32 v141, 0xffff0000, v135
	v_lshlrev_b32_e32 v135, 16, v136
	v_mul_f32_e32 v135, 0xbfb8aa3b, v135
	v_exp_f32_e32 v135, v135
	v_lshlrev_b32_e32 v138, 16, v134
	v_and_b32_e32 v139, 0xffff0000, v134
	v_and_b32_e32 v142, 0xffff0000, v136
	v_add_f32_e32 v135, 1.0, v135
	v_mul_f32_e32 v134, 0xbfb8aa3b, v138
	v_rcp_f32_e32 v136, v135
	v_mul_f32_e32 v135, 0xbfb8aa3b, v139
	v_exp_f32_e32 v134, v134
	v_exp_f32_e32 v135, v135
	v_lshlrev_b32_e32 v138, 16, v120
	v_and_b32_e32 v139, 0xffff0000, v120
	v_mul_f32_e32 v120, 0xbfb8aa3b, v142
	v_exp_f32_e32 v120, v120
	v_add_f32_e32 v134, 1.0, v134
	v_add_f32_e32 v135, 1.0, v135
	v_rcp_f32_e32 v134, v134
	v_rcp_f32_e32 v135, v135
	v_add_f32_e32 v120, 1.0, v120
	v_lshlrev_b32_e32 v143, 16, v137
	v_and_b32_e32 v144, 0xffff0000, v137
	v_rcp_f32_e32 v137, v120
	v_pk_fma_f32 v[60:61], v[60:61], v[134:135], v[138:139]
	v_lshlrev_b32_e32 v134, 16, v122
	v_and_b32_e32 v135, 0xffff0000, v122
	v_pk_fma_f32 v[134:135], v[56:57], v[136:137], v[134:135]
	v_mul_f32_e32 v57, 0xbfb8aa3b, v143
	v_exp_f32_e32 v57, v57
	v_mul_f32_e32 v56, 0xbfb8aa3b, v140
	v_exp_f32_e32 v56, v56
	v_lshlrev_b32_e32 v136, 16, v121
	v_add_f32_e32 v57, 1.0, v57
	v_rcp_f32_e32 v120, v57
	v_mul_f32_e32 v57, 0xbfb8aa3b, v141
	v_exp_f32_e32 v57, v57
	v_add_f32_e32 v56, 1.0, v56
	v_rcp_f32_e32 v56, v56
	v_and_b32_e32 v137, 0xffff0000, v121
	v_add_f32_e32 v57, 1.0, v57
	v_rcp_f32_e32 v57, v57
	s_nop 0
	v_pk_fma_f32 v[62:63], v[62:63], v[56:57], v[136:137]
	v_mul_f32_e32 v56, 0xbfb8aa3b, v144
	v_exp_f32_e32 v56, v56
	v_and_b32_e32 v57, 0xffff0000, v123
	v_add_f32_e32 v56, 1.0, v56
	v_rcp_f32_e32 v121, v56
	v_lshlrev_b32_e32 v56, 16, v123
	v_pk_fma_f32 v[120:121], v[58:59], v[120:121], v[56:57]
	v_cvt_pk_bf16_f32 v56, v60, v61
	v_lshl_add_u64 v[60:61], s[78:79], 0, v[130:131]
	v_cvt_pk_bf16_f32 v57, v62, v63
	v_cvt_pk_bf16_f32 v58, v134, v135
	v_cvt_pk_bf16_f32 v59, v120, v121
	v_lshl_add_u64 v[60:61], v[60:61], 0, v[132:133]
	global_store_dwordx4 v[60:61], v[56:59], off
	v_lshlrev_b32_e32 v62, 16, v112
	v_and_b32_e32 v63, 0xffff0000, v112
	v_lshlrev_b32_e32 v56, 16, v116
	v_and_b32_e32 v57, 0xffff0000, v116
	v_mul_f32_e32 v56, 0xbfb8aa3b, v56
	v_mul_f32_e32 v57, 0xbfb8aa3b, v57
	v_exp_f32_e32 v56, v56
	v_exp_f32_e32 v57, v57
	v_lshlrev_b32_e32 v58, 16, v118
	v_and_b32_e32 v59, 0xffff0000, v118
	v_add_f32_e32 v56, 1.0, v56
	v_add_f32_e32 v57, 1.0, v57
	v_rcp_f32_e32 v56, v56
	v_rcp_f32_e32 v57, v57
	v_mul_f32_e32 v58, 0xbfb8aa3b, v58
	v_exp_f32_e32 v58, v58
	v_lshlrev_b32_e32 v118, 16, v119
	v_pk_fma_f32 v[52:53], v[52:53], v[56:57], v[62:63]
	v_mul_f32_e32 v56, 0xbfb8aa3b, v59
	v_exp_f32_e32 v56, v56
	v_add_f32_e32 v58, 1.0, v58
	v_rcp_f32_e32 v58, v58
	v_and_b32_e32 v57, 0xffff0000, v114
	v_add_f32_e32 v56, 1.0, v56
	v_rcp_f32_e32 v59, v56
	v_lshlrev_b32_e32 v56, 16, v114
	v_lshlrev_b32_e32 v116, 16, v117
	v_and_b32_e32 v117, 0xffff0000, v117
	v_pk_fma_f32 v[56:57], v[48:49], v[58:59], v[56:57]
	v_mul_f32_e32 v49, 0xbfb8aa3b, v118
	v_exp_f32_e32 v49, v49
	v_mul_f32_e32 v48, 0xbfb8aa3b, v116
	v_exp_f32_e32 v48, v48
	v_and_b32_e32 v119, 0xffff0000, v119
	v_add_f32_e32 v49, 1.0, v49
	v_rcp_f32_e32 v58, v49
	v_mul_f32_e32 v49, 0xbfb8aa3b, v117
	v_exp_f32_e32 v49, v49
	v_add_f32_e32 v48, 1.0, v48
	v_rcp_f32_e32 v48, v48
	v_lshlrev_b32_e32 v62, 16, v113
	v_add_f32_e32 v49, 1.0, v49
	v_rcp_f32_e32 v49, v49
	v_and_b32_e32 v63, 0xffff0000, v113
	v_pk_fma_f32 v[54:55], v[54:55], v[48:49], v[62:63]
	v_mul_f32_e32 v48, 0xbfb8aa3b, v119
	v_exp_f32_e32 v48, v48
	v_and_b32_e32 v49, 0xffff0000, v115
	v_add_f32_e32 v48, 1.0, v48
	v_rcp_f32_e32 v59, v48
	v_lshlrev_b32_e32 v48, 16, v115
	v_pk_fma_f32 v[58:59], v[50:51], v[58:59], v[48:49]
	v_cvt_pk_bf16_f32 v48, v52, v53
	v_cvt_pk_bf16_f32 v49, v54, v55
	v_cvt_pk_bf16_f32 v50, v56, v57
	v_cvt_pk_bf16_f32 v51, v58, v59
	global_store_dwordx4 v[60:61], v[48:51], off offset:256
	v_lshlrev_b32_e32 v52, 16, v110
	v_and_b32_e32 v53, 0xffff0000, v110
	v_lshlrev_b32_e32 v50, 16, v108
	v_and_b32_e32 v51, 0xffff0000, v108
	v_mul_f32_e32 v50, 0xbfb8aa3b, v50
	v_mul_f32_e32 v51, 0xbfb8aa3b, v51
	v_exp_f32_e32 v50, v50
	v_exp_f32_e32 v51, v51
	v_lshlrev_b32_e32 v54, 16, v104
	v_and_b32_e32 v55, 0xffff0000, v104
	v_add_f32_e32 v50, 1.0, v50
	v_add_f32_e32 v51, 1.0, v51
	v_rcp_f32_e32 v50, v50
	v_rcp_f32_e32 v51, v51
	v_mul_f32_e32 v52, 0xbfb8aa3b, v52
	v_exp_f32_e32 v52, v52
	v_lshlrev_b32_e32 v58, 16, v111
	v_pk_fma_f32 v[44:45], v[44:45], v[50:51], v[54:55]
	v_mul_f32_e32 v50, 0xbfb8aa3b, v53
	v_exp_f32_e32 v50, v50
	v_add_f32_e32 v52, 1.0, v52
	v_rcp_f32_e32 v52, v52
	v_and_b32_e32 v51, 0xffff0000, v106
	v_add_f32_e32 v50, 1.0, v50
	v_rcp_f32_e32 v53, v50
	v_lshlrev_b32_e32 v50, 16, v106
	v_lshlrev_b32_e32 v56, 16, v109
	v_and_b32_e32 v57, 0xffff0000, v109
	v_pk_fma_f32 v[50:51], v[40:41], v[52:53], v[50:51]
	v_mul_f32_e32 v41, 0xbfb8aa3b, v58
	v_exp_f32_e32 v41, v41
	v_mul_f32_e32 v40, 0xbfb8aa3b, v56
	v_exp_f32_e32 v40, v40
	v_and_b32_e32 v59, 0xffff0000, v111
	v_add_f32_e32 v41, 1.0, v41
	v_rcp_f32_e32 v52, v41
	v_mul_f32_e32 v41, 0xbfb8aa3b, v57
	v_exp_f32_e32 v41, v41
	v_add_f32_e32 v40, 1.0, v40
	v_rcp_f32_e32 v40, v40
	v_lshlrev_b32_e32 v54, 16, v105
	v_add_f32_e32 v41, 1.0, v41
	v_rcp_f32_e32 v41, v41
	v_and_b32_e32 v55, 0xffff0000, v105
	v_lshlrev_b64 v[48:49], 11, v[128:129]
	v_pk_fma_f32 v[46:47], v[46:47], v[40:41], v[54:55]
	v_mul_f32_e32 v40, 0xbfb8aa3b, v59
	v_exp_f32_e32 v40, v40
	v_and_b32_e32 v41, 0xffff0000, v107
	v_add_f32_e32 v40, 1.0, v40
	v_rcp_f32_e32 v53, v40
	v_lshlrev_b32_e32 v40, 16, v107
	v_pk_fma_f32 v[52:53], v[42:43], v[52:53], v[40:41]
	v_cvt_pk_bf16_f32 v40, v44, v45
	v_lshl_add_u64 v[44:45], s[78:79], 0, v[48:49]
	v_cvt_pk_bf16_f32 v41, v46, v47
	v_cvt_pk_bf16_f32 v42, v50, v51
	v_cvt_pk_bf16_f32 v43, v52, v53
	v_lshl_add_u64 v[44:45], v[44:45], 0, v[132:133]
	global_store_dwordx4 v[44:45], v[40:43], off
	v_lshlrev_b32_e32 v46, 16, v96
	v_and_b32_e32 v47, 0xffff0000, v96
	v_lshlrev_b32_e32 v40, 16, v100
	v_and_b32_e32 v41, 0xffff0000, v100
	v_mul_f32_e32 v40, 0xbfb8aa3b, v40
	v_mul_f32_e32 v41, 0xbfb8aa3b, v41
	v_exp_f32_e32 v40, v40
	v_exp_f32_e32 v41, v41
	v_lshlrev_b32_e32 v42, 16, v102
	v_and_b32_e32 v43, 0xffff0000, v102
	v_add_f32_e32 v40, 1.0, v40
	v_add_f32_e32 v41, 1.0, v41
	v_rcp_f32_e32 v40, v40
	v_rcp_f32_e32 v41, v41
	v_mul_f32_e32 v42, 0xbfb8aa3b, v42
	v_exp_f32_e32 v42, v42
	v_lshlrev_b32_e32 v50, 16, v103
	v_pk_fma_f32 v[36:37], v[36:37], v[40:41], v[46:47]
	v_mul_f32_e32 v40, 0xbfb8aa3b, v43
	v_exp_f32_e32 v40, v40
	v_add_f32_e32 v42, 1.0, v42
	v_rcp_f32_e32 v42, v42
	v_and_b32_e32 v41, 0xffff0000, v98
	v_add_f32_e32 v40, 1.0, v40
	v_rcp_f32_e32 v43, v40
	v_lshlrev_b32_e32 v40, 16, v98
	v_lshlrev_b32_e32 v48, 16, v101
	v_and_b32_e32 v49, 0xffff0000, v101
	v_pk_fma_f32 v[40:41], v[32:33], v[42:43], v[40:41]
	v_mul_f32_e32 v33, 0xbfb8aa3b, v50
	v_exp_f32_e32 v33, v33
	v_mul_f32_e32 v32, 0xbfb8aa3b, v48
	v_exp_f32_e32 v32, v32
	v_and_b32_e32 v51, 0xffff0000, v103
	v_add_f32_e32 v33, 1.0, v33
	v_rcp_f32_e32 v42, v33
	v_mul_f32_e32 v33, 0xbfb8aa3b, v49
	v_exp_f32_e32 v33, v33
	v_add_f32_e32 v32, 1.0, v32
	v_rcp_f32_e32 v32, v32
	v_lshlrev_b32_e32 v46, 16, v97
	v_add_f32_e32 v33, 1.0, v33
	v_rcp_f32_e32 v33, v33
	v_and_b32_e32 v47, 0xffff0000, v97
	v_pk_fma_f32 v[38:39], v[38:39], v[32:33], v[46:47]
	v_mul_f32_e32 v32, 0xbfb8aa3b, v51
	v_exp_f32_e32 v32, v32
	v_and_b32_e32 v33, 0xffff0000, v99
	v_add_f32_e32 v32, 1.0, v32
	v_rcp_f32_e32 v43, v32
	v_lshlrev_b32_e32 v32, 16, v99
	v_pk_fma_f32 v[42:43], v[34:35], v[42:43], v[32:33]
	v_cvt_pk_bf16_f32 v32, v36, v37
	v_cvt_pk_bf16_f32 v33, v38, v39
	v_cvt_pk_bf16_f32 v34, v40, v41
	v_cvt_pk_bf16_f32 v35, v42, v43
	global_store_dwordx4 v[44:45], v[32:35], off offset:256
	v_lshlrev_b32_e32 v36, 16, v94
	v_and_b32_e32 v37, 0xffff0000, v94
	v_lshlrev_b32_e32 v34, 16, v92
	v_and_b32_e32 v35, 0xffff0000, v92
	v_mul_f32_e32 v34, 0xbfb8aa3b, v34
	v_mul_f32_e32 v35, 0xbfb8aa3b, v35
	v_exp_f32_e32 v34, v34
	v_exp_f32_e32 v35, v35
	v_lshlrev_b32_e32 v38, 16, v88
	v_and_b32_e32 v39, 0xffff0000, v88
	v_add_f32_e32 v34, 1.0, v34
	v_add_f32_e32 v35, 1.0, v35
	v_rcp_f32_e32 v34, v34
	v_rcp_f32_e32 v35, v35
	v_mul_f32_e32 v36, 0xbfb8aa3b, v36
	v_exp_f32_e32 v36, v36
	v_lshlrev_b32_e32 v42, 16, v95
	v_pk_fma_f32 v[28:29], v[28:29], v[34:35], v[38:39]
	v_mul_f32_e32 v34, 0xbfb8aa3b, v37
	v_exp_f32_e32 v34, v34
	v_add_f32_e32 v36, 1.0, v36
	v_rcp_f32_e32 v36, v36
	v_and_b32_e32 v35, 0xffff0000, v90
	v_add_f32_e32 v34, 1.0, v34
	v_rcp_f32_e32 v37, v34
	v_lshlrev_b32_e32 v34, 16, v90
	v_lshlrev_b32_e32 v40, 16, v93
	v_and_b32_e32 v41, 0xffff0000, v93
	v_pk_fma_f32 v[34:35], v[24:25], v[36:37], v[34:35]
	v_mul_f32_e32 v25, 0xbfb8aa3b, v42
	v_exp_f32_e32 v25, v25
	v_mul_f32_e32 v24, 0xbfb8aa3b, v40
	v_exp_f32_e32 v24, v24
	v_and_b32_e32 v43, 0xffff0000, v95
	v_add_f32_e32 v25, 1.0, v25
	v_rcp_f32_e32 v36, v25
	v_mul_f32_e32 v25, 0xbfb8aa3b, v41
	v_exp_f32_e32 v25, v25
	v_add_f32_e32 v24, 1.0, v24
	v_rcp_f32_e32 v24, v24
	v_lshlrev_b32_e32 v38, 16, v89
	v_add_f32_e32 v25, 1.0, v25
	v_rcp_f32_e32 v25, v25
	v_and_b32_e32 v39, 0xffff0000, v89
	v_lshlrev_b64 v[32:33], 11, v[126:127]
	v_pk_fma_f32 v[30:31], v[30:31], v[24:25], v[38:39]
	v_mul_f32_e32 v24, 0xbfb8aa3b, v43
	v_exp_f32_e32 v24, v24
	v_and_b32_e32 v25, 0xffff0000, v91
	v_add_f32_e32 v24, 1.0, v24
	v_rcp_f32_e32 v37, v24
	v_lshlrev_b32_e32 v24, 16, v91
	v_pk_fma_f32 v[36:37], v[26:27], v[36:37], v[24:25]
	v_cvt_pk_bf16_f32 v24, v28, v29
	v_lshl_add_u64 v[28:29], s[78:79], 0, v[32:33]
	v_cvt_pk_bf16_f32 v25, v30, v31
	v_cvt_pk_bf16_f32 v26, v34, v35
	v_cvt_pk_bf16_f32 v27, v36, v37
	v_lshl_add_u64 v[28:29], v[28:29], 0, v[132:133]
	global_store_dwordx4 v[28:29], v[24:27], off
	v_lshlrev_b32_e32 v30, 16, v80
	v_and_b32_e32 v31, 0xffff0000, v80
	v_lshlrev_b32_e32 v24, 16, v84
	v_and_b32_e32 v25, 0xffff0000, v84
	v_mul_f32_e32 v24, 0xbfb8aa3b, v24
	v_mul_f32_e32 v25, 0xbfb8aa3b, v25
	v_exp_f32_e32 v24, v24
	v_exp_f32_e32 v25, v25
	v_lshlrev_b32_e32 v26, 16, v86
	v_and_b32_e32 v27, 0xffff0000, v86
	v_add_f32_e32 v24, 1.0, v24
	v_add_f32_e32 v25, 1.0, v25
	v_rcp_f32_e32 v24, v24
	v_rcp_f32_e32 v25, v25
	v_mul_f32_e32 v26, 0xbfb8aa3b, v26
	v_exp_f32_e32 v26, v26
	v_lshlrev_b32_e32 v34, 16, v87
	v_pk_fma_f32 v[20:21], v[20:21], v[24:25], v[30:31]
	v_mul_f32_e32 v24, 0xbfb8aa3b, v27
	v_exp_f32_e32 v24, v24
	v_add_f32_e32 v26, 1.0, v26
	v_rcp_f32_e32 v26, v26
	v_and_b32_e32 v25, 0xffff0000, v82
	v_add_f32_e32 v24, 1.0, v24
	v_rcp_f32_e32 v27, v24
	v_lshlrev_b32_e32 v24, 16, v82
	v_lshlrev_b32_e32 v32, 16, v85
	v_and_b32_e32 v33, 0xffff0000, v85
	v_pk_fma_f32 v[24:25], v[16:17], v[26:27], v[24:25]
	v_mul_f32_e32 v17, 0xbfb8aa3b, v34
	v_exp_f32_e32 v17, v17
	v_mul_f32_e32 v16, 0xbfb8aa3b, v32
	v_exp_f32_e32 v16, v16
	v_and_b32_e32 v35, 0xffff0000, v87
	v_add_f32_e32 v17, 1.0, v17
	v_rcp_f32_e32 v26, v17
	v_mul_f32_e32 v17, 0xbfb8aa3b, v33
	v_exp_f32_e32 v17, v17
	v_add_f32_e32 v16, 1.0, v16
	v_rcp_f32_e32 v16, v16
	v_lshlrev_b32_e32 v30, 16, v81
	v_add_f32_e32 v17, 1.0, v17
	v_rcp_f32_e32 v17, v17
	v_and_b32_e32 v31, 0xffff0000, v81
	v_pk_fma_f32 v[22:23], v[22:23], v[16:17], v[30:31]
	v_mul_f32_e32 v16, 0xbfb8aa3b, v35
	v_exp_f32_e32 v16, v16
	v_and_b32_e32 v17, 0xffff0000, v83
	v_add_f32_e32 v16, 1.0, v16
	v_rcp_f32_e32 v27, v16
	v_lshlrev_b32_e32 v16, 16, v83
	v_pk_fma_f32 v[26:27], v[18:19], v[26:27], v[16:17]
	v_cvt_pk_bf16_f32 v16, v20, v21
	v_cvt_pk_bf16_f32 v17, v22, v23
	v_cvt_pk_bf16_f32 v18, v24, v25
	v_cvt_pk_bf16_f32 v19, v26, v27
	global_store_dwordx4 v[28:29], v[16:19], off offset:256
	v_lshlrev_b32_e32 v20, 16, v78
	v_and_b32_e32 v21, 0xffff0000, v78
	v_lshlrev_b32_e32 v18, 16, v76
	v_and_b32_e32 v19, 0xffff0000, v76
	v_mul_f32_e32 v18, 0xbfb8aa3b, v18
	v_mul_f32_e32 v19, 0xbfb8aa3b, v19
	v_exp_f32_e32 v18, v18
	v_exp_f32_e32 v19, v19
	v_lshlrev_b32_e32 v22, 16, v72
	v_and_b32_e32 v23, 0xffff0000, v72
	v_add_f32_e32 v18, 1.0, v18
	v_add_f32_e32 v19, 1.0, v19
	v_rcp_f32_e32 v18, v18
	v_rcp_f32_e32 v19, v19
	v_mul_f32_e32 v20, 0xbfb8aa3b, v20
	v_exp_f32_e32 v20, v20
	v_lshlrev_b32_e32 v26, 16, v79
	v_pk_fma_f32 v[12:13], v[12:13], v[18:19], v[22:23]
	v_mul_f32_e32 v18, 0xbfb8aa3b, v21
	v_exp_f32_e32 v18, v18
	v_add_f32_e32 v20, 1.0, v20
	v_rcp_f32_e32 v20, v20
	v_and_b32_e32 v19, 0xffff0000, v74
	v_add_f32_e32 v18, 1.0, v18
	v_rcp_f32_e32 v21, v18
	v_lshlrev_b32_e32 v18, 16, v74
	v_lshlrev_b32_e32 v24, 16, v77
	v_and_b32_e32 v25, 0xffff0000, v77
	v_pk_fma_f32 v[18:19], v[8:9], v[20:21], v[18:19]
	v_mul_f32_e32 v9, 0xbfb8aa3b, v26
	v_exp_f32_e32 v9, v9
	v_mul_f32_e32 v8, 0xbfb8aa3b, v24
	v_exp_f32_e32 v8, v8
	v_and_b32_e32 v27, 0xffff0000, v79
	v_add_f32_e32 v9, 1.0, v9
	v_rcp_f32_e32 v20, v9
	v_mul_f32_e32 v9, 0xbfb8aa3b, v25
	v_exp_f32_e32 v9, v9
	v_add_f32_e32 v8, 1.0, v8
	v_rcp_f32_e32 v8, v8
	v_lshlrev_b32_e32 v22, 16, v73
	v_add_f32_e32 v9, 1.0, v9
	v_rcp_f32_e32 v9, v9
	v_and_b32_e32 v23, 0xffff0000, v73
	v_lshlrev_b64 v[16:17], 11, v[124:125]
	v_pk_fma_f32 v[14:15], v[14:15], v[8:9], v[22:23]
	v_mul_f32_e32 v8, 0xbfb8aa3b, v27
	v_exp_f32_e32 v8, v8
	v_and_b32_e32 v9, 0xffff0000, v75
	v_add_f32_e32 v8, 1.0, v8
	v_rcp_f32_e32 v21, v8
	v_lshlrev_b32_e32 v8, 16, v75
	v_pk_fma_f32 v[20:21], v[10:11], v[20:21], v[8:9]
	v_cvt_pk_bf16_f32 v8, v12, v13
	v_lshl_add_u64 v[12:13], s[78:79], 0, v[16:17]
	v_cvt_pk_bf16_f32 v9, v14, v15
	v_cvt_pk_bf16_f32 v10, v18, v19
	v_cvt_pk_bf16_f32 v11, v20, v21
	v_lshl_add_u64 v[12:13], v[12:13], 0, v[132:133]
	global_store_dwordx4 v[12:13], v[8:11], off
	v_lshlrev_b32_e32 v14, 16, v64
	v_and_b32_e32 v15, 0xffff0000, v64
	v_lshlrev_b32_e32 v8, 16, v68
	v_and_b32_e32 v9, 0xffff0000, v68
	v_mul_f32_e32 v8, 0xbfb8aa3b, v8
	v_mul_f32_e32 v9, 0xbfb8aa3b, v9
	v_exp_f32_e32 v8, v8
	v_exp_f32_e32 v9, v9
	v_lshlrev_b32_e32 v10, 16, v70
	v_and_b32_e32 v11, 0xffff0000, v70
	v_add_f32_e32 v8, 1.0, v8
	v_add_f32_e32 v9, 1.0, v9
	v_rcp_f32_e32 v8, v8
	v_rcp_f32_e32 v9, v9
	v_mul_f32_e32 v10, 0xbfb8aa3b, v10
	v_exp_f32_e32 v10, v10
	v_lshlrev_b32_e32 v18, 16, v71
	v_pk_fma_f32 v[4:5], v[4:5], v[8:9], v[14:15]
	v_mul_f32_e32 v8, 0xbfb8aa3b, v11
	v_exp_f32_e32 v8, v8
	v_add_f32_e32 v10, 1.0, v10
	v_rcp_f32_e32 v10, v10
	v_and_b32_e32 v9, 0xffff0000, v66
	v_add_f32_e32 v8, 1.0, v8
	v_rcp_f32_e32 v11, v8
	v_lshlrev_b32_e32 v8, 16, v66
	v_lshlrev_b32_e32 v16, 16, v69
	v_and_b32_e32 v17, 0xffff0000, v69
	v_pk_fma_f32 v[8:9], v[0:1], v[10:11], v[8:9]
	v_mul_f32_e32 v1, 0xbfb8aa3b, v18
	v_exp_f32_e32 v1, v1
	v_mul_f32_e32 v0, 0xbfb8aa3b, v16
	v_exp_f32_e32 v0, v0
	v_and_b32_e32 v19, 0xffff0000, v71
	v_add_f32_e32 v1, 1.0, v1
	v_rcp_f32_e32 v10, v1
	v_mul_f32_e32 v1, 0xbfb8aa3b, v17
	v_exp_f32_e32 v1, v1
	v_add_f32_e32 v0, 1.0, v0
	v_rcp_f32_e32 v0, v0
	v_lshlrev_b32_e32 v14, 16, v65
	v_add_f32_e32 v1, 1.0, v1
	v_rcp_f32_e32 v1, v1
	v_and_b32_e32 v15, 0xffff0000, v65
	v_pk_fma_f32 v[6:7], v[6:7], v[0:1], v[14:15]
	v_mul_f32_e32 v0, 0xbfb8aa3b, v19
	v_exp_f32_e32 v0, v0
	v_and_b32_e32 v1, 0xffff0000, v67
	v_add_f32_e32 v0, 1.0, v0
	v_rcp_f32_e32 v11, v0
	v_lshlrev_b32_e32 v0, 16, v67
	v_pk_fma_f32 v[10:11], v[2:3], v[10:11], v[0:1]
	v_cvt_pk_bf16_f32 v0, v4, v5
	v_cvt_pk_bf16_f32 v1, v6, v7
	v_cvt_pk_bf16_f32 v2, v8, v9
	v_cvt_pk_bf16_f32 v3, v10, v11
	global_store_dwordx4 v[12:13], v[0:3], off offset:256
	s_cbranch_vccnz .LBB0_584
	s_andn2_b64 vcc, exec, s[12:13]
	s_cbranch_vccnz .LBB0_583
	s_barrier
	s_branch .LBB0_583
